# GEMM unit loops: first K-iteration peeled with SrcC=0 on the first MFMA of every accumulator; the 128 v_mov accumulator clears per unit are gone
# speedup vs baseline: 1.0071x; 1.0071x over previous
.LBB0_257:
	s_ashr_i32 s31, s30, 31
	s_lshl_b64 s[34:35], s[30:31], 19
	s_add_u32 s34, s48, s34
	s_addc_u32 s35, s49, s35
	s_and_b64 s[36:37], s[6:7], exec
	s_cselect_b32 s31, s35, s39
	s_cselect_b32 s47, s34, s38
	s_ashr_i32 s29, s28, 31
	s_lshl_b64 s[36:37], s[28:29], 19
	s_add_u32 s36, s50, s36
	s_addc_u32 s37, s51, s37
	s_and_b64 s[56:57], s[6:7], exec
	s_cselect_b32 s29, s37, s9
	s_cselect_b32 s87, s36, s8
	s_add_u32 s88, s8, 0x100
	s_addc_u32 s89, s9, 0
	s_add_u32 s8, s38, 0x40080
	s_addc_u32 s9, s39, 0
	s_mov_b32 s90, -2
	s_add_u32 s38, s8, 0xfffc0080
	s_addc_u32 s39, s9, -1
	s_add_i32 s91, 0, 0x10000
	s_cmp_eq_u32 s90, 12
	s_cselect_b32 s57, s31, s39
	s_cselect_b32 s56, s47, s38
	s_cselect_b32 s39, s29, s89
	s_cselect_b32 s38, s87, s88
	s_add_i32 s94, 0, 0x14000
	v_add_u32_e32 v140, s91, v183
	v_add_u32_e32 v168, s94, v183
	ds_read_b128 v[128:131], v140
	ds_read_b128 v[132:135], v140 offset:1024
	ds_read_b128 v[136:139], v140 offset:2048
	ds_read_b128 v[140:143], v140 offset:3072
	ds_read_b128 v[144:147], v168
	ds_read_b128 v[148:151], v168 offset:1024
	ds_read_b128 v[164:167], v168 offset:2048
	ds_read_b128 v[168:171], v168 offset:3072
	v_lshl_add_u64 v[184:185], s[8:9], 0, v[162:163]
	s_add_i32 m0, s55, 0xc000
	ds_read_b128 v[172:175], v187
	ds_read_b128 v[176:179], v187 offset:1024
	ds_read_b128 v[188:191], v187 offset:2048
	ds_read_b128 v[202:205], v187 offset:3072
	ds_read_b128 v[206:209], v187 offset:4096
	ds_read_b128 v[210:213], v187 offset:5120
	ds_read_b128 v[214:217], v187 offset:6144
	ds_read_b128 v[218:221], v187 offset:7168
	global_load_lds_dwordx4 v[184:185], off
	v_lshl_add_u64 v[184:185], s[8:9], 0, v[160:161]
	s_add_i32 m0, s55, 0xe000
	s_nop 0
	global_load_lds_dwordx4 v[184:185], off
	s_waitcnt vmcnt(8)
	s_waitcnt lgkmcnt(0)
	s_barrier
	s_setprio 1
	s_waitcnt lgkmcnt(0)
	v_mfma_f32_16x16x32_bf16 v[124:127], v[128:131], v[172:175], 0
	v_mfma_f32_16x16x32_bf16 v[120:123], v[136:139], v[172:175], 0
	v_mfma_f32_16x16x32_bf16 v[112:115], v[128:131], v[188:191], 0
	v_mfma_f32_16x16x32_bf16 v[104:107], v[136:139], v[188:191], 0
	v_mfma_f32_16x16x32_bf16 v[96:99], v[128:131], v[206:209], 0
	v_mfma_f32_16x16x32_bf16 v[88:91], v[136:139], v[206:209], 0
	v_mfma_f32_16x16x32_bf16 v[80:83], v[128:131], v[214:217], 0
	v_mfma_f32_16x16x32_bf16 v[72:75], v[136:139], v[214:217], 0
	v_mfma_f32_16x16x32_bf16 v[124:127], v[132:135], v[176:179], v[124:127]
	v_mfma_f32_16x16x32_bf16 v[120:123], v[140:143], v[176:179], v[120:123]
	v_mfma_f32_16x16x32_bf16 v[112:115], v[132:135], v[202:205], v[112:115]
	v_mfma_f32_16x16x32_bf16 v[104:107], v[140:143], v[202:205], v[104:107]
	v_mfma_f32_16x16x32_bf16 v[96:99], v[132:135], v[210:213], v[96:99]
	v_mfma_f32_16x16x32_bf16 v[88:91], v[140:143], v[210:213], v[88:91]
	v_mfma_f32_16x16x32_bf16 v[80:83], v[132:135], v[218:221], v[80:83]
	v_mfma_f32_16x16x32_bf16 v[72:75], v[140:143], v[218:221], v[72:75]
	s_setprio 0
	s_setprio 1
	v_mfma_f32_16x16x32_bf16 v[116:119], v[144:147], v[172:175], 0
	v_mfma_f32_16x16x32_bf16 v[108:111], v[164:167], v[172:175], 0
	v_mfma_f32_16x16x32_bf16 v[100:103], v[144:147], v[188:191], 0
	v_mfma_f32_16x16x32_bf16 v[92:95], v[164:167], v[188:191], 0
	v_mfma_f32_16x16x32_bf16 v[84:87], v[144:147], v[206:209], 0
	v_mfma_f32_16x16x32_bf16 v[76:79], v[164:167], v[206:209], 0
	v_mfma_f32_16x16x32_bf16 v[68:71], v[144:147], v[214:217], 0
	v_mfma_f32_16x16x32_bf16 v[64:67], v[164:167], v[214:217], 0
	v_mfma_f32_16x16x32_bf16 v[116:119], v[148:151], v[176:179], v[116:119]
	v_mfma_f32_16x16x32_bf16 v[108:111], v[168:171], v[176:179], v[108:111]
	v_mfma_f32_16x16x32_bf16 v[100:103], v[148:151], v[202:205], v[100:103]
	v_mfma_f32_16x16x32_bf16 v[92:95], v[168:171], v[202:205], v[92:95]
	v_mfma_f32_16x16x32_bf16 v[84:87], v[148:151], v[210:213], v[84:87]
	v_mfma_f32_16x16x32_bf16 v[76:79], v[168:171], v[210:213], v[76:79]
	v_mfma_f32_16x16x32_bf16 v[68:71], v[148:151], v[218:221], v[68:71]
	v_mfma_f32_16x16x32_bf16 v[64:67], v[168:171], v[218:221], v[64:67]
	s_setprio 0
	s_barrier
	s_add_i32 s91, s91, s54
	v_lshl_add_u64 v[184:185], s[38:39], 0, v[192:193]
	s_mov_b32 m0, s91
	ds_read_b128 v[172:175], v187 offset:16384
	ds_read_b128 v[176:179], v187 offset:17408
	ds_read_b128 v[188:191], v187 offset:18432
	ds_read_b128 v[202:205], v187 offset:19456
	ds_read_b128 v[206:209], v187 offset:20480
	ds_read_b128 v[210:213], v187 offset:21504
	ds_read_b128 v[214:217], v187 offset:22528
	ds_read_b128 v[218:221], v187 offset:23552
	global_load_lds_dwordx4 v[184:185], off
	s_add_i32 m0, s91, 0x2000
	s_add_u32 s92, s38, 0x40000
	v_lshl_add_u64 v[222:223], s[38:39], 0, v[152:153]
	s_addc_u32 s93, s39, 0
	s_add_i32 s91, s94, s54
	global_load_lds_dwordx4 v[222:223], off
	v_lshl_add_u64 v[224:225], s[92:93], 0, v[192:193]
	s_mov_b32 m0, s91
	v_lshl_add_u64 v[226:227], s[56:57], 0, v[154:155]
	global_load_lds_dwordx4 v[224:225], off
	v_lshl_add_u64 v[224:225], s[92:93], 0, v[152:153]
	s_add_i32 m0, s91, 0x2000
	s_nop 0
	global_load_lds_dwordx4 v[224:225], off
	v_lshl_add_u64 v[224:225], s[56:57], 0, v[156:157]
	s_mov_b32 m0, s55
	s_nop 0
	global_load_lds_dwordx4 v[224:225], off
	s_mov_b32 m0, s60
	s_nop 0
	global_load_lds_dwordx4 v[226:227], off
	s_waitcnt vmcnt(8)
	s_waitcnt lgkmcnt(0)
	s_barrier
	s_setprio 1
	s_waitcnt lgkmcnt(0)
	v_mfma_f32_16x16x32_bf16 v[60:63], v[128:131], v[172:175], 0
	v_mfma_f32_16x16x32_bf16 v[56:59], v[136:139], v[172:175], 0
	v_mfma_f32_16x16x32_bf16 v[48:51], v[128:131], v[188:191], 0
	v_mfma_f32_16x16x32_bf16 v[40:43], v[136:139], v[188:191], 0
	v_mfma_f32_16x16x32_bf16 v[32:35], v[128:131], v[206:209], 0
	v_mfma_f32_16x16x32_bf16 v[24:27], v[136:139], v[206:209], 0
	v_mfma_f32_16x16x32_bf16 v[16:19], v[128:131], v[214:217], 0
	v_mfma_f32_16x16x32_bf16 v[8:11], v[136:139], v[214:217], 0
	v_mfma_f32_16x16x32_bf16 v[60:63], v[132:135], v[176:179], v[60:63]
	v_mfma_f32_16x16x32_bf16 v[56:59], v[140:143], v[176:179], v[56:59]
	v_mfma_f32_16x16x32_bf16 v[48:51], v[132:135], v[202:205], v[48:51]
	v_mfma_f32_16x16x32_bf16 v[40:43], v[140:143], v[202:205], v[40:43]
	v_mfma_f32_16x16x32_bf16 v[32:35], v[132:135], v[210:213], v[32:35]
	v_mfma_f32_16x16x32_bf16 v[24:27], v[140:143], v[210:213], v[24:27]
	v_mfma_f32_16x16x32_bf16 v[16:19], v[132:135], v[218:221], v[16:19]
	v_mfma_f32_16x16x32_bf16 v[8:11], v[140:143], v[218:221], v[8:11]
	s_setprio 0
	s_setprio 1
	v_mfma_f32_16x16x32_bf16 v[52:55], v[144:147], v[172:175], 0
	v_mfma_f32_16x16x32_bf16 v[44:47], v[164:167], v[172:175], 0
	v_mfma_f32_16x16x32_bf16 v[36:39], v[144:147], v[188:191], 0
	v_mfma_f32_16x16x32_bf16 v[28:31], v[164:167], v[188:191], 0
	v_mfma_f32_16x16x32_bf16 v[20:23], v[144:147], v[206:209], 0
	v_mfma_f32_16x16x32_bf16 v[12:15], v[164:167], v[206:209], 0
	v_mfma_f32_16x16x32_bf16 v[4:7], v[144:147], v[214:217], 0
	v_mfma_f32_16x16x32_bf16 v[0:3], v[164:167], v[214:217], 0
	v_mfma_f32_16x16x32_bf16 v[52:55], v[148:151], v[176:179], v[52:55]
	v_mfma_f32_16x16x32_bf16 v[44:47], v[168:171], v[176:179], v[44:47]
	v_mfma_f32_16x16x32_bf16 v[36:39], v[148:151], v[202:205], v[36:39]
	v_mfma_f32_16x16x32_bf16 v[28:31], v[168:171], v[202:205], v[28:31]
	v_mfma_f32_16x16x32_bf16 v[20:23], v[148:151], v[210:213], v[20:23]
	v_mfma_f32_16x16x32_bf16 v[12:15], v[168:171], v[210:213], v[12:15]
	v_mfma_f32_16x16x32_bf16 v[4:7], v[148:151], v[218:221], v[4:7]
	v_mfma_f32_16x16x32_bf16 v[0:3], v[168:171], v[218:221], v[0:3]
	s_setprio 0
	s_barrier
	s_add_i32 s91, 0, 0x18000
	s_add_i32 s92, 0, 0x1c000
	v_add_u32_e32 v140, s91, v183
	v_add_u32_e32 v168, s92, v183
	ds_read_b128 v[128:131], v140
	ds_read_b128 v[132:135], v140 offset:1024
	ds_read_b128 v[136:139], v140 offset:2048
	ds_read_b128 v[140:143], v140 offset:3072
	ds_read_b128 v[144:147], v168
	ds_read_b128 v[148:151], v168 offset:1024
	ds_read_b128 v[164:167], v168 offset:2048
	ds_read_b128 v[168:171], v168 offset:3072
	s_add_u32 s56, s56, 0x40000
	s_addc_u32 s57, s57, 0
	s_mov_b32 m0, s61
	v_lshl_add_u64 v[228:229], s[56:57], 0, v[156:157]
	ds_read_b128 v[172:175], v187 offset:32768
	ds_read_b128 v[176:179], v187 offset:33792
	ds_read_b128 v[188:191], v187 offset:34816
	ds_read_b128 v[202:205], v187 offset:35840
	ds_read_b128 v[206:209], v187 offset:36864
	ds_read_b128 v[210:213], v187 offset:37888
	ds_read_b128 v[214:217], v187 offset:38912
	ds_read_b128 v[218:221], v187 offset:39936
	global_load_lds_dwordx4 v[228:229], off
	v_lshl_add_u64 v[228:229], s[56:57], 0, v[154:155]
	s_mov_b32 m0, s82
	s_nop 0
	global_load_lds_dwordx4 v[228:229], off
	s_waitcnt vmcnt(8)
	s_waitcnt lgkmcnt(0)
	s_barrier
	s_setprio 1
	s_waitcnt lgkmcnt(0)
	v_mfma_f32_16x16x32_bf16 v[124:127], v[128:131], v[172:175], v[124:127]
	v_mfma_f32_16x16x32_bf16 v[120:123], v[136:139], v[172:175], v[120:123]
	v_mfma_f32_16x16x32_bf16 v[112:115], v[128:131], v[188:191], v[112:115]
	v_mfma_f32_16x16x32_bf16 v[104:107], v[136:139], v[188:191], v[104:107]
	v_mfma_f32_16x16x32_bf16 v[96:99], v[128:131], v[206:209], v[96:99]
	v_mfma_f32_16x16x32_bf16 v[88:91], v[136:139], v[206:209], v[88:91]
	v_mfma_f32_16x16x32_bf16 v[80:83], v[128:131], v[214:217], v[80:83]
	v_mfma_f32_16x16x32_bf16 v[72:75], v[136:139], v[214:217], v[72:75]
	v_mfma_f32_16x16x32_bf16 v[124:127], v[132:135], v[176:179], v[124:127]
	v_mfma_f32_16x16x32_bf16 v[120:123], v[140:143], v[176:179], v[120:123]
	v_mfma_f32_16x16x32_bf16 v[112:115], v[132:135], v[202:205], v[112:115]
	v_mfma_f32_16x16x32_bf16 v[104:107], v[140:143], v[202:205], v[104:107]
	v_mfma_f32_16x16x32_bf16 v[96:99], v[132:135], v[210:213], v[96:99]
	v_mfma_f32_16x16x32_bf16 v[88:91], v[140:143], v[210:213], v[88:91]
	v_mfma_f32_16x16x32_bf16 v[80:83], v[132:135], v[218:221], v[80:83]
	v_mfma_f32_16x16x32_bf16 v[72:75], v[140:143], v[218:221], v[72:75]
	s_setprio 0
	s_setprio 1
	v_mfma_f32_16x16x32_bf16 v[116:119], v[144:147], v[172:175], v[116:119]
	v_mfma_f32_16x16x32_bf16 v[108:111], v[164:167], v[172:175], v[108:111]
	v_mfma_f32_16x16x32_bf16 v[100:103], v[144:147], v[188:191], v[100:103]
	v_mfma_f32_16x16x32_bf16 v[92:95], v[164:167], v[188:191], v[92:95]
	v_mfma_f32_16x16x32_bf16 v[84:87], v[144:147], v[206:209], v[84:87]
	v_mfma_f32_16x16x32_bf16 v[76:79], v[164:167], v[206:209], v[76:79]
	v_mfma_f32_16x16x32_bf16 v[68:71], v[144:147], v[214:217], v[68:71]
	v_mfma_f32_16x16x32_bf16 v[64:67], v[164:167], v[214:217], v[64:67]
	v_mfma_f32_16x16x32_bf16 v[116:119], v[148:151], v[176:179], v[116:119]
	v_mfma_f32_16x16x32_bf16 v[108:111], v[168:171], v[176:179], v[108:111]
	v_mfma_f32_16x16x32_bf16 v[100:103], v[148:151], v[202:205], v[100:103]
	v_mfma_f32_16x16x32_bf16 v[92:95], v[168:171], v[202:205], v[92:95]
	v_mfma_f32_16x16x32_bf16 v[84:87], v[148:151], v[210:213], v[84:87]
	v_mfma_f32_16x16x32_bf16 v[76:79], v[168:171], v[210:213], v[76:79]
	v_mfma_f32_16x16x32_bf16 v[68:71], v[148:151], v[218:221], v[68:71]
	v_mfma_f32_16x16x32_bf16 v[64:67], v[168:171], v[218:221], v[64:67]
	s_setprio 0
	s_barrier
	s_add_i32 s56, s91, s54
	v_lshl_add_u64 v[184:185], v[184:185], 0, s[76:77]
	s_mov_b32 m0, s56
	ds_read_b128 v[172:175], v187 offset:49152
	ds_read_b128 v[176:179], v187 offset:50176
	ds_read_b128 v[188:191], v187 offset:51200
	ds_read_b128 v[202:205], v187 offset:52224
	ds_read_b128 v[206:209], v187 offset:53248
	ds_read_b128 v[210:213], v187 offset:54272
	ds_read_b128 v[214:217], v187 offset:55296
	ds_read_b128 v[218:221], v187 offset:56320
	global_load_lds_dwordx4 v[184:185], off
	s_add_i32 m0, s56, 0x2000
	s_add_u32 s38, s38, 0x40080
	v_lshl_add_u64 v[184:185], v[222:223], 0, s[76:77]
	s_addc_u32 s39, s39, 0
	s_add_i32 s56, s92, s54
	global_load_lds_dwordx4 v[184:185], off
	v_lshl_add_u64 v[184:185], s[38:39], 0, v[192:193]
	s_mov_b32 m0, s56
	s_nop 0
	global_load_lds_dwordx4 v[184:185], off
	v_lshl_add_u64 v[184:185], s[38:39], 0, v[152:153]
	s_add_i32 m0, s56, 0x2000
	s_nop 0
	global_load_lds_dwordx4 v[184:185], off
	v_lshl_add_u64 v[184:185], v[224:225], 0, s[76:77]
	s_mov_b32 m0, s68
	s_nop 0
	global_load_lds_dwordx4 v[184:185], off
	v_lshl_add_u64 v[184:185], v[226:227], 0, s[76:77]
	s_mov_b32 m0, s83
	s_nop 0
	global_load_lds_dwordx4 v[184:185], off
	s_waitcnt vmcnt(8)
	s_waitcnt lgkmcnt(0)
	s_barrier
	s_setprio 1
	s_waitcnt lgkmcnt(0)
	v_mfma_f32_16x16x32_bf16 v[60:63], v[128:131], v[172:175], v[60:63]
	v_mfma_f32_16x16x32_bf16 v[56:59], v[136:139], v[172:175], v[56:59]
	v_mfma_f32_16x16x32_bf16 v[48:51], v[128:131], v[188:191], v[48:51]
	v_mfma_f32_16x16x32_bf16 v[40:43], v[136:139], v[188:191], v[40:43]
	v_mfma_f32_16x16x32_bf16 v[32:35], v[128:131], v[206:209], v[32:35]
	v_mfma_f32_16x16x32_bf16 v[24:27], v[136:139], v[206:209], v[24:27]
	v_mfma_f32_16x16x32_bf16 v[16:19], v[128:131], v[214:217], v[16:19]
	v_mfma_f32_16x16x32_bf16 v[8:11], v[136:139], v[214:217], v[8:11]
	v_mfma_f32_16x16x32_bf16 v[60:63], v[132:135], v[176:179], v[60:63]
	v_mfma_f32_16x16x32_bf16 v[56:59], v[140:143], v[176:179], v[56:59]
	v_mfma_f32_16x16x32_bf16 v[48:51], v[132:135], v[202:205], v[48:51]
	v_mfma_f32_16x16x32_bf16 v[40:43], v[140:143], v[202:205], v[40:43]
	v_mfma_f32_16x16x32_bf16 v[32:35], v[132:135], v[210:213], v[32:35]
	v_mfma_f32_16x16x32_bf16 v[24:27], v[140:143], v[210:213], v[24:27]
	v_mfma_f32_16x16x32_bf16 v[16:19], v[132:135], v[218:221], v[16:19]
	v_mfma_f32_16x16x32_bf16 v[8:11], v[140:143], v[218:221], v[8:11]
	s_setprio 0
	s_setprio 1
	v_mfma_f32_16x16x32_bf16 v[52:55], v[144:147], v[172:175], v[52:55]
	v_mfma_f32_16x16x32_bf16 v[44:47], v[164:167], v[172:175], v[44:47]
	v_mfma_f32_16x16x32_bf16 v[36:39], v[144:147], v[188:191], v[36:39]
	v_mfma_f32_16x16x32_bf16 v[28:31], v[164:167], v[188:191], v[28:31]
	v_mfma_f32_16x16x32_bf16 v[20:23], v[144:147], v[206:209], v[20:23]
	v_mfma_f32_16x16x32_bf16 v[12:15], v[164:167], v[206:209], v[12:15]
	v_mfma_f32_16x16x32_bf16 v[4:7], v[144:147], v[214:217], v[4:7]
	v_mfma_f32_16x16x32_bf16 v[0:3], v[164:167], v[214:217], v[0:3]
	v_mfma_f32_16x16x32_bf16 v[52:55], v[148:151], v[176:179], v[52:55]
	v_mfma_f32_16x16x32_bf16 v[44:47], v[168:171], v[176:179], v[44:47]
	v_mfma_f32_16x16x32_bf16 v[36:39], v[148:151], v[202:205], v[36:39]
	v_mfma_f32_16x16x32_bf16 v[28:31], v[168:171], v[202:205], v[28:31]
	v_mfma_f32_16x16x32_bf16 v[20:23], v[148:151], v[210:213], v[20:23]
	v_mfma_f32_16x16x32_bf16 v[12:15], v[168:171], v[210:213], v[12:15]
	v_mfma_f32_16x16x32_bf16 v[4:7], v[148:151], v[218:221], v[4:7]
	v_mfma_f32_16x16x32_bf16 v[0:3], v[168:171], v[218:221], v[0:3]
	s_setprio 0
	s_barrier
	s_add_i32 s90, s90, 2
	s_add_u32 s88, s88, 0x100
	s_addc_u32 s89, s89, 0
	s_add_u32 s8, s8, 0x100
	s_addc_u32 s9, s9, 0
	s_cmp_gt_u32 s90, 13

.LBB0_858:
	s_ashr_i32 s23, s22, 31
	s_lshl_b64 s[24:25], s[22:23], 19
	s_add_u32 s24, s36, s24
	s_addc_u32 s25, s37, s25
	s_and_b64 s[26:27], s[8:9], exec
	s_cselect_b32 s23, s25, s31
	s_cselect_b32 s61, s24, s30
	s_ashr_i32 s21, s20, 31
	s_lshl_b64 s[26:27], s[20:21], 19
	s_add_u32 s26, s38, s26
	s_addc_u32 s27, s39, s27
	s_and_b64 s[34:35], s[8:9], exec
	s_cselect_b32 s21, s27, s29
	s_cselect_b32 s68, s26, s28
	s_add_u32 s82, s28, 0x100
	s_addc_u32 s83, s29, 0
	s_add_u32 s28, s30, 0x40080
	s_addc_u32 s29, s31, 0
	s_mov_b32 s85, -2
	s_waitcnt lgkmcnt(0)
	s_add_u32 s30, s28, 0xfffc0080
	s_addc_u32 s31, s29, -1
	s_add_i32 s86, 0, 0x10000
	s_cmp_eq_u32 s85, 12
	s_cselect_b32 s35, s23, s31
	s_cselect_b32 s34, s61, s30
	s_cselect_b32 s31, s21, s83
	s_cselect_b32 s30, s68, s82
	s_add_i32 s88, 0, 0x14000
	v_add_u32_e32 v124, s86, v248
	v_add_u32_e32 v156, s88, v248
	ds_read_b128 v[88:91], v124
	ds_read_b128 v[100:103], v124 offset:1024
	ds_read_b128 v[112:115], v124 offset:2048
	ds_read_b128 v[124:127], v124 offset:3072
	ds_read_b128 v[136:139], v156
	ds_read_b128 v[140:143], v156 offset:1024
	ds_read_b128 v[148:151], v156 offset:2048
	ds_read_b128 v[156:159], v156 offset:3072
	v_lshl_add_u64 v[212:213], s[28:29], 0, v[210:211]
	s_add_i32 m0, s47, 0xc000
	ds_read_b128 v[160:163], v250
	ds_read_b128 v[164:167], v250 offset:1024
	ds_read_b128 v[168:171], v250 offset:2048
	ds_read_b128 v[172:175], v250 offset:3072
	ds_read_b128 v[176:179], v250 offset:4096
	ds_read_b128 v[180:183], v250 offset:5120
	ds_read_b128 v[184:187], v250 offset:6144
	ds_read_b128 v[188:191], v250 offset:7168
	global_load_lds_dwordx4 v[212:213], off
	v_lshl_add_u64 v[212:213], s[28:29], 0, v[208:209]
	s_add_i32 m0, s47, 0xe000
	s_nop 0
	global_load_lds_dwordx4 v[212:213], off
	s_waitcnt vmcnt(8)
	s_waitcnt lgkmcnt(0)
	s_barrier
	s_setprio 1
	s_waitcnt lgkmcnt(0)
	v_mfma_f32_16x16x32_bf16 v[152:155], v[88:91], v[160:163], 0
	v_mfma_f32_16x16x32_bf16 v[144:147], v[112:115], v[160:163], 0
	v_mfma_f32_16x16x32_bf16 v[120:123], v[88:91], v[168:171], 0
	v_mfma_f32_16x16x32_bf16 v[116:119], v[112:115], v[168:171], 0
	v_mfma_f32_16x16x32_bf16 v[96:99], v[88:91], v[176:179], 0
	v_mfma_f32_16x16x32_bf16 v[92:95], v[112:115], v[176:179], 0
	v_mfma_f32_16x16x32_bf16 v[76:79], v[88:91], v[184:187], 0
	v_mfma_f32_16x16x32_bf16 v[72:75], v[112:115], v[184:187], 0
	v_mfma_f32_16x16x32_bf16 v[152:155], v[100:103], v[164:167], v[152:155]
	v_mfma_f32_16x16x32_bf16 v[144:147], v[124:127], v[164:167], v[144:147]
	v_mfma_f32_16x16x32_bf16 v[120:123], v[100:103], v[172:175], v[120:123]
	v_mfma_f32_16x16x32_bf16 v[116:119], v[124:127], v[172:175], v[116:119]
	v_mfma_f32_16x16x32_bf16 v[96:99], v[100:103], v[180:183], v[96:99]
	v_mfma_f32_16x16x32_bf16 v[92:95], v[124:127], v[180:183], v[92:95]
	v_mfma_f32_16x16x32_bf16 v[76:79], v[100:103], v[188:191], v[76:79]
	v_mfma_f32_16x16x32_bf16 v[72:75], v[124:127], v[188:191], v[72:75]
	s_setprio 0
	s_setprio 1
	v_mfma_f32_16x16x32_bf16 v[132:135], v[136:139], v[160:163], 0
	v_mfma_f32_16x16x32_bf16 v[128:131], v[148:151], v[160:163], 0
	v_mfma_f32_16x16x32_bf16 v[108:111], v[136:139], v[168:171], 0
	v_mfma_f32_16x16x32_bf16 v[104:107], v[148:151], v[168:171], 0
	v_mfma_f32_16x16x32_bf16 v[84:87], v[136:139], v[176:179], 0
	v_mfma_f32_16x16x32_bf16 v[80:83], v[148:151], v[176:179], 0
	v_mfma_f32_16x16x32_bf16 v[68:71], v[136:139], v[184:187], 0
	v_mfma_f32_16x16x32_bf16 v[64:67], v[148:151], v[184:187], 0
	v_mfma_f32_16x16x32_bf16 v[132:135], v[140:143], v[164:167], v[132:135]
	v_mfma_f32_16x16x32_bf16 v[128:131], v[156:159], v[164:167], v[128:131]
	v_mfma_f32_16x16x32_bf16 v[108:111], v[140:143], v[172:175], v[108:111]
	v_mfma_f32_16x16x32_bf16 v[104:107], v[156:159], v[172:175], v[104:107]
	v_mfma_f32_16x16x32_bf16 v[84:87], v[140:143], v[180:183], v[84:87]
	v_mfma_f32_16x16x32_bf16 v[80:83], v[156:159], v[180:183], v[80:83]
	v_mfma_f32_16x16x32_bf16 v[68:71], v[140:143], v[188:191], v[68:71]
	v_mfma_f32_16x16x32_bf16 v[64:67], v[156:159], v[188:191], v[64:67]
	s_setprio 0
	s_barrier
	s_add_i32 s86, s86, s46
	v_lshl_add_u64 v[212:213], s[30:31], 0, v[192:193]
	s_mov_b32 m0, s86
	ds_read_b128 v[160:163], v250 offset:16384
	ds_read_b128 v[164:167], v250 offset:17408
	ds_read_b128 v[168:171], v250 offset:18432
	ds_read_b128 v[172:175], v250 offset:19456
	ds_read_b128 v[176:179], v250 offset:20480
	ds_read_b128 v[180:183], v250 offset:21504
	ds_read_b128 v[184:187], v250 offset:22528
	ds_read_b128 v[188:191], v250 offset:23552
	global_load_lds_dwordx4 v[212:213], off
	s_add_i32 m0, s86, 0x2000
	s_add_u32 s86, s30, 0x40000
	v_lshl_add_u64 v[214:215], s[30:31], 0, v[202:203]
	s_addc_u32 s87, s31, 0
	s_add_i32 s88, s88, s46
	global_load_lds_dwordx4 v[214:215], off
	v_lshl_add_u64 v[216:217], s[86:87], 0, v[192:193]
	s_mov_b32 m0, s88
	v_lshl_add_u64 v[218:219], s[34:35], 0, v[204:205]
	global_load_lds_dwordx4 v[216:217], off
	v_lshl_add_u64 v[216:217], s[86:87], 0, v[202:203]
	s_add_i32 m0, s88, 0x2000
	s_nop 0
	global_load_lds_dwordx4 v[216:217], off
	v_lshl_add_u64 v[216:217], s[34:35], 0, v[206:207]
	s_mov_b32 m0, s47
	s_nop 0
	global_load_lds_dwordx4 v[216:217], off
	s_mov_b32 m0, s48
	s_nop 0
	global_load_lds_dwordx4 v[218:219], off
	s_waitcnt vmcnt(8)
	s_waitcnt lgkmcnt(0)
	s_barrier
	s_setprio 1
	s_waitcnt lgkmcnt(0)
	v_mfma_f32_16x16x32_bf16 v[60:63], v[88:91], v[160:163], 0
	v_mfma_f32_16x16x32_bf16 v[56:59], v[112:115], v[160:163], 0
	v_mfma_f32_16x16x32_bf16 v[44:47], v[88:91], v[168:171], 0
	v_mfma_f32_16x16x32_bf16 v[40:43], v[112:115], v[168:171], 0
	v_mfma_f32_16x16x32_bf16 v[28:31], v[88:91], v[176:179], 0
	v_mfma_f32_16x16x32_bf16 v[24:27], v[112:115], v[176:179], 0
	v_mfma_f32_16x16x32_bf16 v[12:15], v[88:91], v[184:187], 0
	v_mfma_f32_16x16x32_bf16 v[8:11], v[112:115], v[184:187], 0
	v_mfma_f32_16x16x32_bf16 v[60:63], v[100:103], v[164:167], v[60:63]
	v_mfma_f32_16x16x32_bf16 v[56:59], v[124:127], v[164:167], v[56:59]
	v_mfma_f32_16x16x32_bf16 v[44:47], v[100:103], v[172:175], v[44:47]
	v_mfma_f32_16x16x32_bf16 v[40:43], v[124:127], v[172:175], v[40:43]
	v_mfma_f32_16x16x32_bf16 v[28:31], v[100:103], v[180:183], v[28:31]
	v_mfma_f32_16x16x32_bf16 v[24:27], v[124:127], v[180:183], v[24:27]
	v_mfma_f32_16x16x32_bf16 v[12:15], v[100:103], v[188:191], v[12:15]
	v_mfma_f32_16x16x32_bf16 v[8:11], v[124:127], v[188:191], v[8:11]
	s_setprio 0
	s_setprio 1
	v_mfma_f32_16x16x32_bf16 v[52:55], v[136:139], v[160:163], 0
	v_mfma_f32_16x16x32_bf16 v[48:51], v[148:151], v[160:163], 0
	v_mfma_f32_16x16x32_bf16 v[36:39], v[136:139], v[168:171], 0
	v_mfma_f32_16x16x32_bf16 v[32:35], v[148:151], v[168:171], 0
	v_mfma_f32_16x16x32_bf16 v[20:23], v[136:139], v[176:179], 0
	v_mfma_f32_16x16x32_bf16 v[16:19], v[148:151], v[176:179], 0
	v_mfma_f32_16x16x32_bf16 v[4:7], v[136:139], v[184:187], 0
	v_mfma_f32_16x16x32_bf16 v[0:3], v[148:151], v[184:187], 0
	v_mfma_f32_16x16x32_bf16 v[52:55], v[140:143], v[164:167], v[52:55]
	v_mfma_f32_16x16x32_bf16 v[48:51], v[156:159], v[164:167], v[48:51]
	v_mfma_f32_16x16x32_bf16 v[36:39], v[140:143], v[172:175], v[36:39]
	v_mfma_f32_16x16x32_bf16 v[32:35], v[156:159], v[172:175], v[32:35]
	v_mfma_f32_16x16x32_bf16 v[20:23], v[140:143], v[180:183], v[20:23]
	v_mfma_f32_16x16x32_bf16 v[16:19], v[156:159], v[180:183], v[16:19]
	v_mfma_f32_16x16x32_bf16 v[4:7], v[140:143], v[188:191], v[4:7]
	v_mfma_f32_16x16x32_bf16 v[0:3], v[156:159], v[188:191], v[0:3]
	s_setprio 0
	s_barrier
	s_add_i32 s86, 0, 0x18000
	s_add_i32 s87, 0, 0x1c000
	v_add_u32_e32 v124, s86, v248
	v_add_u32_e32 v156, s87, v248
	ds_read_b128 v[88:91], v124
	ds_read_b128 v[100:103], v124 offset:1024
	ds_read_b128 v[112:115], v124 offset:2048
	ds_read_b128 v[124:127], v124 offset:3072
	ds_read_b128 v[136:139], v156
	ds_read_b128 v[140:143], v156 offset:1024
	ds_read_b128 v[148:151], v156 offset:2048
	ds_read_b128 v[156:159], v156 offset:3072
	s_add_u32 s34, s34, 0x40000
	s_addc_u32 s35, s35, 0
	s_mov_b32 m0, s49
	v_lshl_add_u64 v[220:221], s[34:35], 0, v[206:207]
	ds_read_b128 v[160:163], v250 offset:32768
	ds_read_b128 v[164:167], v250 offset:33792
	ds_read_b128 v[168:171], v250 offset:34816
	ds_read_b128 v[172:175], v250 offset:35840
	ds_read_b128 v[176:179], v250 offset:36864
	ds_read_b128 v[180:183], v250 offset:37888
	ds_read_b128 v[184:187], v250 offset:38912
	ds_read_b128 v[188:191], v250 offset:39936
	global_load_lds_dwordx4 v[220:221], off
	v_lshl_add_u64 v[220:221], s[34:35], 0, v[204:205]
	s_mov_b32 m0, s50
	s_nop 0
	global_load_lds_dwordx4 v[220:221], off
	s_waitcnt vmcnt(8)
	s_waitcnt lgkmcnt(0)
	s_barrier
	s_setprio 1
	s_waitcnt lgkmcnt(0)
	v_mfma_f32_16x16x32_bf16 v[152:155], v[88:91], v[160:163], v[152:155]
	v_mfma_f32_16x16x32_bf16 v[144:147], v[112:115], v[160:163], v[144:147]
	v_mfma_f32_16x16x32_bf16 v[120:123], v[88:91], v[168:171], v[120:123]
	v_mfma_f32_16x16x32_bf16 v[116:119], v[112:115], v[168:171], v[116:119]
	v_mfma_f32_16x16x32_bf16 v[96:99], v[88:91], v[176:179], v[96:99]
	v_mfma_f32_16x16x32_bf16 v[92:95], v[112:115], v[176:179], v[92:95]
	v_mfma_f32_16x16x32_bf16 v[76:79], v[88:91], v[184:187], v[76:79]
	v_mfma_f32_16x16x32_bf16 v[72:75], v[112:115], v[184:187], v[72:75]
	v_mfma_f32_16x16x32_bf16 v[152:155], v[100:103], v[164:167], v[152:155]
	v_mfma_f32_16x16x32_bf16 v[144:147], v[124:127], v[164:167], v[144:147]
	v_mfma_f32_16x16x32_bf16 v[120:123], v[100:103], v[172:175], v[120:123]
	v_mfma_f32_16x16x32_bf16 v[116:119], v[124:127], v[172:175], v[116:119]
	v_mfma_f32_16x16x32_bf16 v[96:99], v[100:103], v[180:183], v[96:99]
	v_mfma_f32_16x16x32_bf16 v[92:95], v[124:127], v[180:183], v[92:95]
	v_mfma_f32_16x16x32_bf16 v[76:79], v[100:103], v[188:191], v[76:79]
	v_mfma_f32_16x16x32_bf16 v[72:75], v[124:127], v[188:191], v[72:75]
	s_setprio 0
	s_setprio 1
	v_mfma_f32_16x16x32_bf16 v[132:135], v[136:139], v[160:163], v[132:135]
	v_mfma_f32_16x16x32_bf16 v[128:131], v[148:151], v[160:163], v[128:131]
	v_mfma_f32_16x16x32_bf16 v[108:111], v[136:139], v[168:171], v[108:111]
	v_mfma_f32_16x16x32_bf16 v[104:107], v[148:151], v[168:171], v[104:107]
	v_mfma_f32_16x16x32_bf16 v[84:87], v[136:139], v[176:179], v[84:87]
	v_mfma_f32_16x16x32_bf16 v[80:83], v[148:151], v[176:179], v[80:83]
	v_mfma_f32_16x16x32_bf16 v[68:71], v[136:139], v[184:187], v[68:71]
	v_mfma_f32_16x16x32_bf16 v[64:67], v[148:151], v[184:187], v[64:67]
	v_mfma_f32_16x16x32_bf16 v[132:135], v[140:143], v[164:167], v[132:135]
	v_mfma_f32_16x16x32_bf16 v[128:131], v[156:159], v[164:167], v[128:131]
	v_mfma_f32_16x16x32_bf16 v[108:111], v[140:143], v[172:175], v[108:111]
	v_mfma_f32_16x16x32_bf16 v[104:107], v[156:159], v[172:175], v[104:107]
	v_mfma_f32_16x16x32_bf16 v[84:87], v[140:143], v[180:183], v[84:87]
	v_mfma_f32_16x16x32_bf16 v[80:83], v[156:159], v[180:183], v[80:83]
	v_mfma_f32_16x16x32_bf16 v[68:71], v[140:143], v[188:191], v[68:71]
	v_mfma_f32_16x16x32_bf16 v[64:67], v[156:159], v[188:191], v[64:67]
	s_setprio 0
	s_barrier
	s_add_i32 s34, s86, s46
	v_lshl_add_u64 v[212:213], v[212:213], 0, s[76:77]
	s_mov_b32 m0, s34
	ds_read_b128 v[160:163], v250 offset:49152
	ds_read_b128 v[164:167], v250 offset:50176
	ds_read_b128 v[168:171], v250 offset:51200
	ds_read_b128 v[172:175], v250 offset:52224
	ds_read_b128 v[176:179], v250 offset:53248
	ds_read_b128 v[180:183], v250 offset:54272
	ds_read_b128 v[184:187], v250 offset:55296
	ds_read_b128 v[188:191], v250 offset:56320
	global_load_lds_dwordx4 v[212:213], off
	s_add_i32 m0, s34, 0x2000
	s_add_u32 s30, s30, 0x40080
	v_lshl_add_u64 v[212:213], v[214:215], 0, s[76:77]
	s_addc_u32 s31, s31, 0
	s_add_i32 s34, s87, s46
	global_load_lds_dwordx4 v[212:213], off
	v_lshl_add_u64 v[212:213], s[30:31], 0, v[192:193]
	s_mov_b32 m0, s34
	s_nop 0
	global_load_lds_dwordx4 v[212:213], off
	v_lshl_add_u64 v[212:213], s[30:31], 0, v[202:203]
	s_add_i32 m0, s34, 0x2000
	s_nop 0
	global_load_lds_dwordx4 v[212:213], off
	v_lshl_add_u64 v[212:213], v[216:217], 0, s[76:77]
	s_mov_b32 m0, s54
	s_nop 0
	global_load_lds_dwordx4 v[212:213], off
	v_lshl_add_u64 v[212:213], v[218:219], 0, s[76:77]
	s_mov_b32 m0, s55
	s_nop 0
	global_load_lds_dwordx4 v[212:213], off
	s_waitcnt vmcnt(8)
	s_waitcnt lgkmcnt(0)
	s_barrier
	s_setprio 1
	s_waitcnt lgkmcnt(0)
	v_mfma_f32_16x16x32_bf16 v[60:63], v[88:91], v[160:163], v[60:63]
	v_mfma_f32_16x16x32_bf16 v[56:59], v[112:115], v[160:163], v[56:59]
	v_mfma_f32_16x16x32_bf16 v[44:47], v[88:91], v[168:171], v[44:47]
	v_mfma_f32_16x16x32_bf16 v[40:43], v[112:115], v[168:171], v[40:43]
	v_mfma_f32_16x16x32_bf16 v[28:31], v[88:91], v[176:179], v[28:31]
	v_mfma_f32_16x16x32_bf16 v[24:27], v[112:115], v[176:179], v[24:27]
	v_mfma_f32_16x16x32_bf16 v[12:15], v[88:91], v[184:187], v[12:15]
	v_mfma_f32_16x16x32_bf16 v[8:11], v[112:115], v[184:187], v[8:11]
	v_mfma_f32_16x16x32_bf16 v[60:63], v[100:103], v[164:167], v[60:63]
	v_mfma_f32_16x16x32_bf16 v[56:59], v[124:127], v[164:167], v[56:59]
	v_mfma_f32_16x16x32_bf16 v[44:47], v[100:103], v[172:175], v[44:47]
	v_mfma_f32_16x16x32_bf16 v[40:43], v[124:127], v[172:175], v[40:43]
	v_mfma_f32_16x16x32_bf16 v[28:31], v[100:103], v[180:183], v[28:31]
	v_mfma_f32_16x16x32_bf16 v[24:27], v[124:127], v[180:183], v[24:27]
	v_mfma_f32_16x16x32_bf16 v[12:15], v[100:103], v[188:191], v[12:15]
	v_mfma_f32_16x16x32_bf16 v[8:11], v[124:127], v[188:191], v[8:11]
	s_setprio 0
	s_setprio 1
	v_mfma_f32_16x16x32_bf16 v[52:55], v[136:139], v[160:163], v[52:55]
	v_mfma_f32_16x16x32_bf16 v[48:51], v[148:151], v[160:163], v[48:51]
	v_mfma_f32_16x16x32_bf16 v[36:39], v[136:139], v[168:171], v[36:39]
	v_mfma_f32_16x16x32_bf16 v[32:35], v[148:151], v[168:171], v[32:35]
	v_mfma_f32_16x16x32_bf16 v[20:23], v[136:139], v[176:179], v[20:23]
	v_mfma_f32_16x16x32_bf16 v[16:19], v[148:151], v[176:179], v[16:19]
	v_mfma_f32_16x16x32_bf16 v[4:7], v[136:139], v[184:187], v[4:7]
	v_mfma_f32_16x16x32_bf16 v[0:3], v[148:151], v[184:187], v[0:3]
	v_mfma_f32_16x16x32_bf16 v[52:55], v[140:143], v[164:167], v[52:55]
	v_mfma_f32_16x16x32_bf16 v[48:51], v[156:159], v[164:167], v[48:51]
	v_mfma_f32_16x16x32_bf16 v[36:39], v[140:143], v[172:175], v[36:39]
	v_mfma_f32_16x16x32_bf16 v[32:35], v[156:159], v[172:175], v[32:35]
	v_mfma_f32_16x16x32_bf16 v[20:23], v[140:143], v[180:183], v[20:23]
	v_mfma_f32_16x16x32_bf16 v[16:19], v[156:159], v[180:183], v[16:19]
	v_mfma_f32_16x16x32_bf16 v[4:7], v[140:143], v[188:191], v[4:7]
	v_mfma_f32_16x16x32_bf16 v[0:3], v[156:159], v[188:191], v[0:3]
	s_setprio 0
	s_barrier
	s_add_i32 s85, s85, 2
	s_add_u32 s82, s82, 0x100
	s_addc_u32 s83, s83, 0
	s_add_u32 s28, s28, 0x100
	s_addc_u32 s29, s29, 0
	s_cmp_gt_u32 s85, 13

.LBB0_934:
	s_ashr_i32 s21, s20, 31
	s_lshl_b64 s[22:23], s[20:21], 19
	s_add_u32 s22, s30, s22
	s_addc_u32 s23, s31, s23
	s_and_b64 s[24:25], s[6:7], exec
	s_cselect_b32 s21, s23, s27
	s_cselect_b32 s54, s22, s26
	s_ashr_i32 s19, s18, 31
	s_lshl_b64 s[24:25], s[18:19], 19
	s_add_u32 s24, s34, s24
	s_addc_u32 s25, s35, s25
	s_and_b64 s[28:29], s[6:7], exec
	s_cselect_b32 s19, s25, s9
	s_cselect_b32 s55, s24, s8
	s_add_u32 s56, s8, 0x100
	s_addc_u32 s57, s9, 0
	s_add_u32 s8, s26, 0x40080
	s_addc_u32 s9, s27, 0
	s_mov_b32 s60, -2
	s_add_u32 s26, s8, 0xfffc0080
	s_addc_u32 s27, s9, -1
	s_add_i32 s61, 0, 0x10000
	s_cmp_eq_u32 s60, 12
	s_cselect_b32 s29, s21, s27
	s_cselect_b32 s28, s54, s26
	s_cselect_b32 s27, s19, s57
	s_cselect_b32 s26, s55, s56
	s_add_i32 s68, 0, 0x14000
	v_add_u32_e32 v140, s61, v185
	v_add_u32_e32 v168, s68, v185
	ds_read_b128 v[128:131], v140
	ds_read_b128 v[132:135], v140 offset:1024
	ds_read_b128 v[136:139], v140 offset:2048
	ds_read_b128 v[140:143], v140 offset:3072
	ds_read_b128 v[144:147], v168
	ds_read_b128 v[148:151], v168 offset:1024
	ds_read_b128 v[164:167], v168 offset:2048
	ds_read_b128 v[168:171], v168 offset:3072
	v_lshl_add_u64 v[180:181], s[8:9], 0, v[162:163]
	s_add_i32 m0, s37, 0xc000
	ds_read_b128 v[172:175], v189
	ds_read_b128 v[176:179], v189 offset:1024
	ds_read_b128 v[202:205], v189 offset:2048
	ds_read_b128 v[206:209], v189 offset:3072
	ds_read_b128 v[210:213], v189 offset:4096
	ds_read_b128 v[214:217], v189 offset:5120
	ds_read_b128 v[218:221], v189 offset:6144
	ds_read_b128 v[222:225], v189 offset:7168
	global_load_lds_dwordx4 v[180:181], off
	v_lshl_add_u64 v[180:181], s[8:9], 0, v[160:161]
	s_add_i32 m0, s37, 0xe000
	s_nop 0
	global_load_lds_dwordx4 v[180:181], off
	s_waitcnt vmcnt(8)
	s_waitcnt lgkmcnt(0)
	s_barrier
	s_setprio 1
	s_waitcnt lgkmcnt(0)
	v_mfma_f32_16x16x32_bf16 v[124:127], v[128:131], v[172:175], 0
	v_mfma_f32_16x16x32_bf16 v[116:119], v[136:139], v[172:175], 0
	v_mfma_f32_16x16x32_bf16 v[108:111], v[128:131], v[202:205], 0
	v_mfma_f32_16x16x32_bf16 v[100:103], v[136:139], v[202:205], 0
	v_mfma_f32_16x16x32_bf16 v[92:95], v[128:131], v[210:213], 0
	v_mfma_f32_16x16x32_bf16 v[84:87], v[136:139], v[210:213], 0
	v_mfma_f32_16x16x32_bf16 v[76:79], v[128:131], v[218:221], 0
	v_mfma_f32_16x16x32_bf16 v[68:71], v[136:139], v[218:221], 0
	v_mfma_f32_16x16x32_bf16 v[124:127], v[132:135], v[176:179], v[124:127]
	v_mfma_f32_16x16x32_bf16 v[116:119], v[140:143], v[176:179], v[116:119]
	v_mfma_f32_16x16x32_bf16 v[108:111], v[132:135], v[206:209], v[108:111]
	v_mfma_f32_16x16x32_bf16 v[100:103], v[140:143], v[206:209], v[100:103]
	v_mfma_f32_16x16x32_bf16 v[92:95], v[132:135], v[214:217], v[92:95]
	v_mfma_f32_16x16x32_bf16 v[84:87], v[140:143], v[214:217], v[84:87]
	v_mfma_f32_16x16x32_bf16 v[76:79], v[132:135], v[222:225], v[76:79]
	v_mfma_f32_16x16x32_bf16 v[68:71], v[140:143], v[222:225], v[68:71]
	s_setprio 0
	s_setprio 1
	v_mfma_f32_16x16x32_bf16 v[120:123], v[144:147], v[172:175], 0
	v_mfma_f32_16x16x32_bf16 v[112:115], v[164:167], v[172:175], 0
	v_mfma_f32_16x16x32_bf16 v[104:107], v[144:147], v[202:205], 0
	v_mfma_f32_16x16x32_bf16 v[96:99], v[164:167], v[202:205], 0
	v_mfma_f32_16x16x32_bf16 v[88:91], v[144:147], v[210:213], 0
	v_mfma_f32_16x16x32_bf16 v[80:83], v[164:167], v[210:213], 0
	v_mfma_f32_16x16x32_bf16 v[72:75], v[144:147], v[218:221], 0
	v_mfma_f32_16x16x32_bf16 v[64:67], v[164:167], v[218:221], 0
	v_mfma_f32_16x16x32_bf16 v[120:123], v[148:151], v[176:179], v[120:123]
	v_mfma_f32_16x16x32_bf16 v[112:115], v[168:171], v[176:179], v[112:115]
	v_mfma_f32_16x16x32_bf16 v[104:107], v[148:151], v[206:209], v[104:107]
	v_mfma_f32_16x16x32_bf16 v[96:99], v[168:171], v[206:209], v[96:99]
	v_mfma_f32_16x16x32_bf16 v[88:91], v[148:151], v[214:217], v[88:91]
	v_mfma_f32_16x16x32_bf16 v[80:83], v[168:171], v[214:217], v[80:83]
	v_mfma_f32_16x16x32_bf16 v[72:75], v[148:151], v[222:225], v[72:75]
	v_mfma_f32_16x16x32_bf16 v[64:67], v[168:171], v[222:225], v[64:67]
	s_setprio 0
	s_barrier
	s_add_i32 s61, s61, s36
	v_lshl_add_u64 v[180:181], s[26:27], 0, v[192:193]
	s_mov_b32 m0, s61
	ds_read_b128 v[172:175], v189 offset:16384
	ds_read_b128 v[176:179], v189 offset:17408
	ds_read_b128 v[202:205], v189 offset:18432
	ds_read_b128 v[206:209], v189 offset:19456
	ds_read_b128 v[210:213], v189 offset:20480
	ds_read_b128 v[214:217], v189 offset:21504
	ds_read_b128 v[218:221], v189 offset:22528
	ds_read_b128 v[222:225], v189 offset:23552
	global_load_lds_dwordx4 v[180:181], off
	s_add_i32 m0, s61, 0x2000
	s_add_u32 s82, s26, 0x40000
	v_lshl_add_u64 v[186:187], s[26:27], 0, v[152:153]
	s_addc_u32 s83, s27, 0
	s_add_i32 s61, s68, s36
	global_load_lds_dwordx4 v[186:187], off
	v_lshl_add_u64 v[190:191], s[82:83], 0, v[192:193]
	s_mov_b32 m0, s61
	v_lshl_add_u64 v[226:227], s[28:29], 0, v[154:155]
	global_load_lds_dwordx4 v[190:191], off
	v_lshl_add_u64 v[190:191], s[82:83], 0, v[152:153]
	s_add_i32 m0, s61, 0x2000
	s_nop 0
	global_load_lds_dwordx4 v[190:191], off
	v_lshl_add_u64 v[190:191], s[28:29], 0, v[156:157]
	s_mov_b32 m0, s37
	s_nop 0
	global_load_lds_dwordx4 v[190:191], off
	s_mov_b32 m0, s38
	s_nop 0
	global_load_lds_dwordx4 v[226:227], off
	s_waitcnt vmcnt(8)
	s_waitcnt lgkmcnt(0)
	s_barrier
	s_setprio 1
	s_waitcnt lgkmcnt(0)
	v_mfma_f32_16x16x32_bf16 v[60:63], v[128:131], v[172:175], 0
	v_mfma_f32_16x16x32_bf16 v[52:55], v[136:139], v[172:175], 0
	v_mfma_f32_16x16x32_bf16 v[44:47], v[128:131], v[202:205], 0
	v_mfma_f32_16x16x32_bf16 v[36:39], v[136:139], v[202:205], 0
	v_mfma_f32_16x16x32_bf16 v[28:31], v[128:131], v[210:213], 0
	v_mfma_f32_16x16x32_bf16 v[20:23], v[136:139], v[210:213], 0
	v_mfma_f32_16x16x32_bf16 v[12:15], v[128:131], v[218:221], 0
	v_mfma_f32_16x16x32_bf16 v[4:7], v[136:139], v[218:221], 0
	v_mfma_f32_16x16x32_bf16 v[60:63], v[132:135], v[176:179], v[60:63]
	v_mfma_f32_16x16x32_bf16 v[52:55], v[140:143], v[176:179], v[52:55]
	v_mfma_f32_16x16x32_bf16 v[44:47], v[132:135], v[206:209], v[44:47]
	v_mfma_f32_16x16x32_bf16 v[36:39], v[140:143], v[206:209], v[36:39]
	v_mfma_f32_16x16x32_bf16 v[28:31], v[132:135], v[214:217], v[28:31]
	v_mfma_f32_16x16x32_bf16 v[20:23], v[140:143], v[214:217], v[20:23]
	v_mfma_f32_16x16x32_bf16 v[12:15], v[132:135], v[222:225], v[12:15]
	v_mfma_f32_16x16x32_bf16 v[4:7], v[140:143], v[222:225], v[4:7]
	s_setprio 0
	s_setprio 1
	v_mfma_f32_16x16x32_bf16 v[56:59], v[144:147], v[172:175], 0
	v_mfma_f32_16x16x32_bf16 v[48:51], v[164:167], v[172:175], 0
	v_mfma_f32_16x16x32_bf16 v[40:43], v[144:147], v[202:205], 0
	v_mfma_f32_16x16x32_bf16 v[32:35], v[164:167], v[202:205], 0
	v_mfma_f32_16x16x32_bf16 v[24:27], v[144:147], v[210:213], 0
	v_mfma_f32_16x16x32_bf16 v[16:19], v[164:167], v[210:213], 0
	v_mfma_f32_16x16x32_bf16 v[8:11], v[144:147], v[218:221], 0
	v_mfma_f32_16x16x32_bf16 v[0:3], v[164:167], v[218:221], 0
	v_mfma_f32_16x16x32_bf16 v[56:59], v[148:151], v[176:179], v[56:59]
	v_mfma_f32_16x16x32_bf16 v[48:51], v[168:171], v[176:179], v[48:51]
	v_mfma_f32_16x16x32_bf16 v[40:43], v[148:151], v[206:209], v[40:43]
	v_mfma_f32_16x16x32_bf16 v[32:35], v[168:171], v[206:209], v[32:35]
	v_mfma_f32_16x16x32_bf16 v[24:27], v[148:151], v[214:217], v[24:27]
	v_mfma_f32_16x16x32_bf16 v[16:19], v[168:171], v[214:217], v[16:19]
	v_mfma_f32_16x16x32_bf16 v[8:11], v[148:151], v[222:225], v[8:11]
	v_mfma_f32_16x16x32_bf16 v[0:3], v[168:171], v[222:225], v[0:3]
	s_setprio 0
	s_barrier
	s_add_i32 s61, 0, 0x18000
	s_add_i32 s68, 0, 0x1c000
	v_add_u32_e32 v140, s61, v185
	v_add_u32_e32 v168, s68, v185
	ds_read_b128 v[128:131], v140
	ds_read_b128 v[132:135], v140 offset:1024
	ds_read_b128 v[136:139], v140 offset:2048
	ds_read_b128 v[140:143], v140 offset:3072
	ds_read_b128 v[144:147], v168
	ds_read_b128 v[148:151], v168 offset:1024
	ds_read_b128 v[164:167], v168 offset:2048
	ds_read_b128 v[168:171], v168 offset:3072
	s_add_u32 s28, s28, 0x40000
	s_addc_u32 s29, s29, 0
	s_mov_b32 m0, s39
	v_lshl_add_u64 v[228:229], s[28:29], 0, v[156:157]
	ds_read_b128 v[172:175], v189 offset:32768
	ds_read_b128 v[176:179], v189 offset:33792
	ds_read_b128 v[202:205], v189 offset:34816
	ds_read_b128 v[206:209], v189 offset:35840
	ds_read_b128 v[210:213], v189 offset:36864
	ds_read_b128 v[214:217], v189 offset:37888
	ds_read_b128 v[218:221], v189 offset:38912
	ds_read_b128 v[222:225], v189 offset:39936
	global_load_lds_dwordx4 v[228:229], off
	v_lshl_add_u64 v[228:229], s[28:29], 0, v[154:155]
	s_mov_b32 m0, s46
	s_nop 0
	global_load_lds_dwordx4 v[228:229], off
	s_waitcnt vmcnt(8)
	s_waitcnt lgkmcnt(0)
	s_barrier
	s_setprio 1
	s_waitcnt lgkmcnt(0)
	v_mfma_f32_16x16x32_bf16 v[124:127], v[128:131], v[172:175], v[124:127]
	v_mfma_f32_16x16x32_bf16 v[116:119], v[136:139], v[172:175], v[116:119]
	v_mfma_f32_16x16x32_bf16 v[108:111], v[128:131], v[202:205], v[108:111]
	v_mfma_f32_16x16x32_bf16 v[100:103], v[136:139], v[202:205], v[100:103]
	v_mfma_f32_16x16x32_bf16 v[92:95], v[128:131], v[210:213], v[92:95]
	v_mfma_f32_16x16x32_bf16 v[84:87], v[136:139], v[210:213], v[84:87]
	v_mfma_f32_16x16x32_bf16 v[76:79], v[128:131], v[218:221], v[76:79]
	v_mfma_f32_16x16x32_bf16 v[68:71], v[136:139], v[218:221], v[68:71]
	v_mfma_f32_16x16x32_bf16 v[124:127], v[132:135], v[176:179], v[124:127]
	v_mfma_f32_16x16x32_bf16 v[116:119], v[140:143], v[176:179], v[116:119]
	v_mfma_f32_16x16x32_bf16 v[108:111], v[132:135], v[206:209], v[108:111]
	v_mfma_f32_16x16x32_bf16 v[100:103], v[140:143], v[206:209], v[100:103]
	v_mfma_f32_16x16x32_bf16 v[92:95], v[132:135], v[214:217], v[92:95]
	v_mfma_f32_16x16x32_bf16 v[84:87], v[140:143], v[214:217], v[84:87]
	v_mfma_f32_16x16x32_bf16 v[76:79], v[132:135], v[222:225], v[76:79]
	v_mfma_f32_16x16x32_bf16 v[68:71], v[140:143], v[222:225], v[68:71]
	s_setprio 0
	s_setprio 1
	v_mfma_f32_16x16x32_bf16 v[120:123], v[144:147], v[172:175], v[120:123]
	v_mfma_f32_16x16x32_bf16 v[112:115], v[164:167], v[172:175], v[112:115]
	v_mfma_f32_16x16x32_bf16 v[104:107], v[144:147], v[202:205], v[104:107]
	v_mfma_f32_16x16x32_bf16 v[96:99], v[164:167], v[202:205], v[96:99]
	v_mfma_f32_16x16x32_bf16 v[88:91], v[144:147], v[210:213], v[88:91]
	v_mfma_f32_16x16x32_bf16 v[80:83], v[164:167], v[210:213], v[80:83]
	v_mfma_f32_16x16x32_bf16 v[72:75], v[144:147], v[218:221], v[72:75]
	v_mfma_f32_16x16x32_bf16 v[64:67], v[164:167], v[218:221], v[64:67]
	v_mfma_f32_16x16x32_bf16 v[120:123], v[148:151], v[176:179], v[120:123]
	v_mfma_f32_16x16x32_bf16 v[112:115], v[168:171], v[176:179], v[112:115]
	v_mfma_f32_16x16x32_bf16 v[104:107], v[148:151], v[206:209], v[104:107]
	v_mfma_f32_16x16x32_bf16 v[96:99], v[168:171], v[206:209], v[96:99]
	v_mfma_f32_16x16x32_bf16 v[88:91], v[148:151], v[214:217], v[88:91]
	v_mfma_f32_16x16x32_bf16 v[80:83], v[168:171], v[214:217], v[80:83]
	v_mfma_f32_16x16x32_bf16 v[72:75], v[148:151], v[222:225], v[72:75]
	v_mfma_f32_16x16x32_bf16 v[64:67], v[168:171], v[222:225], v[64:67]
	s_setprio 0
	s_barrier
	s_add_i32 s28, s61, s36
	v_lshl_add_u64 v[180:181], v[180:181], 0, s[76:77]
	s_mov_b32 m0, s28
	ds_read_b128 v[172:175], v189 offset:49152
	ds_read_b128 v[176:179], v189 offset:50176
	ds_read_b128 v[202:205], v189 offset:51200
	ds_read_b128 v[206:209], v189 offset:52224
	ds_read_b128 v[210:213], v189 offset:53248
	ds_read_b128 v[214:217], v189 offset:54272
	ds_read_b128 v[218:221], v189 offset:55296
	ds_read_b128 v[222:225], v189 offset:56320
	global_load_lds_dwordx4 v[180:181], off
	s_add_i32 m0, s28, 0x2000
	s_add_u32 s26, s26, 0x40080
	v_lshl_add_u64 v[180:181], v[186:187], 0, s[76:77]
	s_addc_u32 s27, s27, 0
	s_add_i32 s28, s68, s36
	global_load_lds_dwordx4 v[180:181], off
	v_lshl_add_u64 v[180:181], s[26:27], 0, v[192:193]
	s_mov_b32 m0, s28
	s_nop 0
	global_load_lds_dwordx4 v[180:181], off
	v_lshl_add_u64 v[180:181], s[26:27], 0, v[152:153]
	s_add_i32 m0, s28, 0x2000
	s_nop 0
	global_load_lds_dwordx4 v[180:181], off
	v_lshl_add_u64 v[180:181], v[190:191], 0, s[76:77]
	s_mov_b32 m0, s47
	s_nop 0
	global_load_lds_dwordx4 v[180:181], off
	v_lshl_add_u64 v[180:181], v[226:227], 0, s[76:77]
	s_mov_b32 m0, s48
	s_nop 0
	global_load_lds_dwordx4 v[180:181], off
	s_waitcnt vmcnt(8)
	s_waitcnt lgkmcnt(0)
	s_barrier
	s_setprio 1
	s_waitcnt lgkmcnt(0)
	v_mfma_f32_16x16x32_bf16 v[60:63], v[128:131], v[172:175], v[60:63]
	v_mfma_f32_16x16x32_bf16 v[52:55], v[136:139], v[172:175], v[52:55]
	v_mfma_f32_16x16x32_bf16 v[44:47], v[128:131], v[202:205], v[44:47]
	v_mfma_f32_16x16x32_bf16 v[36:39], v[136:139], v[202:205], v[36:39]
	v_mfma_f32_16x16x32_bf16 v[28:31], v[128:131], v[210:213], v[28:31]
	v_mfma_f32_16x16x32_bf16 v[20:23], v[136:139], v[210:213], v[20:23]
	v_mfma_f32_16x16x32_bf16 v[12:15], v[128:131], v[218:221], v[12:15]
	v_mfma_f32_16x16x32_bf16 v[4:7], v[136:139], v[218:221], v[4:7]
	v_mfma_f32_16x16x32_bf16 v[60:63], v[132:135], v[176:179], v[60:63]
	v_mfma_f32_16x16x32_bf16 v[52:55], v[140:143], v[176:179], v[52:55]
	v_mfma_f32_16x16x32_bf16 v[44:47], v[132:135], v[206:209], v[44:47]
	v_mfma_f32_16x16x32_bf16 v[36:39], v[140:143], v[206:209], v[36:39]
	v_mfma_f32_16x16x32_bf16 v[28:31], v[132:135], v[214:217], v[28:31]
	v_mfma_f32_16x16x32_bf16 v[20:23], v[140:143], v[214:217], v[20:23]
	v_mfma_f32_16x16x32_bf16 v[12:15], v[132:135], v[222:225], v[12:15]
	v_mfma_f32_16x16x32_bf16 v[4:7], v[140:143], v[222:225], v[4:7]
	s_setprio 0
	s_setprio 1
	v_mfma_f32_16x16x32_bf16 v[56:59], v[144:147], v[172:175], v[56:59]
	v_mfma_f32_16x16x32_bf16 v[48:51], v[164:167], v[172:175], v[48:51]
	v_mfma_f32_16x16x32_bf16 v[40:43], v[144:147], v[202:205], v[40:43]
	v_mfma_f32_16x16x32_bf16 v[32:35], v[164:167], v[202:205], v[32:35]
	v_mfma_f32_16x16x32_bf16 v[24:27], v[144:147], v[210:213], v[24:27]
	v_mfma_f32_16x16x32_bf16 v[16:19], v[164:167], v[210:213], v[16:19]
	v_mfma_f32_16x16x32_bf16 v[8:11], v[144:147], v[218:221], v[8:11]
	v_mfma_f32_16x16x32_bf16 v[0:3], v[164:167], v[218:221], v[0:3]
	v_mfma_f32_16x16x32_bf16 v[56:59], v[148:151], v[176:179], v[56:59]
	v_mfma_f32_16x16x32_bf16 v[48:51], v[168:171], v[176:179], v[48:51]
	v_mfma_f32_16x16x32_bf16 v[40:43], v[148:151], v[206:209], v[40:43]
	v_mfma_f32_16x16x32_bf16 v[32:35], v[168:171], v[206:209], v[32:35]
	v_mfma_f32_16x16x32_bf16 v[24:27], v[148:151], v[214:217], v[24:27]
	v_mfma_f32_16x16x32_bf16 v[16:19], v[168:171], v[214:217], v[16:19]
	v_mfma_f32_16x16x32_bf16 v[8:11], v[148:151], v[222:225], v[8:11]
	v_mfma_f32_16x16x32_bf16 v[0:3], v[168:171], v[222:225], v[0:3]
	s_setprio 0
	s_barrier
	s_add_i32 s60, s60, 2
	s_add_u32 s56, s56, 0x100
	s_addc_u32 s57, s57, 0
	s_add_u32 s8, s8, 0x100
	s_addc_u32 s9, s9, 0
	s_cmp_gt_u32 s60, 13

.LBB0_1003:
	s_add_u32 s56, s24, 0x100
	s_addc_u32 s57, s25, 0
	s_mov_b32 s60, -2
	s_waitcnt lgkmcnt(0)
	s_add_u32 s24, s22, 0x100
	s_addc_u32 s25, s23, 0
	s_add_i32 s61, 0, 0x10000
	s_cmp_eq_u32 s60, 40
	s_cselect_b32 s29, s9, s25
	s_cselect_b32 s28, s8, s24
	s_cselect_b32 s27, s21, s57
	s_cselect_b32 s26, s20, s56
	s_add_i32 s68, 0, 0x14000
	v_add_u32_e32 v124, s61, v248
	v_add_u32_e32 v156, s68, v248
	ds_read_b128 v[88:91], v124
	ds_read_b128 v[100:103], v124 offset:1024
	ds_read_b128 v[112:115], v124 offset:2048
	ds_read_b128 v[124:127], v124 offset:3072
	ds_read_b128 v[136:139], v156
	ds_read_b128 v[140:143], v156 offset:1024
	ds_read_b128 v[148:151], v156 offset:2048
	ds_read_b128 v[156:159], v156 offset:3072
	v_lshl_add_u64 v[212:213], s[22:23], 0, v[210:211]
	s_add_i32 m0, s36, 0xc000
	ds_read_b128 v[160:163], v250
	ds_read_b128 v[164:167], v250 offset:1024
	ds_read_b128 v[168:171], v250 offset:2048
	ds_read_b128 v[172:175], v250 offset:3072
	ds_read_b128 v[176:179], v250 offset:4096
	ds_read_b128 v[180:183], v250 offset:5120
	ds_read_b128 v[184:187], v250 offset:6144
	ds_read_b128 v[188:191], v250 offset:7168
	global_load_lds_dwordx4 v[212:213], off
	v_lshl_add_u64 v[212:213], s[22:23], 0, v[208:209]
	s_add_i32 m0, s36, 0xe000
	s_nop 0
	global_load_lds_dwordx4 v[212:213], off
	s_waitcnt vmcnt(8)
	s_waitcnt lgkmcnt(0)
	s_barrier
	s_setprio 1
	s_waitcnt lgkmcnt(0)
	v_mfma_f32_16x16x32_bf16 v[152:155], v[88:91], v[160:163], 0
	v_mfma_f32_16x16x32_bf16 v[144:147], v[112:115], v[160:163], 0
	v_mfma_f32_16x16x32_bf16 v[120:123], v[88:91], v[168:171], 0
	v_mfma_f32_16x16x32_bf16 v[116:119], v[112:115], v[168:171], 0
	v_mfma_f32_16x16x32_bf16 v[96:99], v[88:91], v[176:179], 0
	v_mfma_f32_16x16x32_bf16 v[92:95], v[112:115], v[176:179], 0
	v_mfma_f32_16x16x32_bf16 v[76:79], v[88:91], v[184:187], 0
	v_mfma_f32_16x16x32_bf16 v[72:75], v[112:115], v[184:187], 0
	v_mfma_f32_16x16x32_bf16 v[152:155], v[100:103], v[164:167], v[152:155]
	v_mfma_f32_16x16x32_bf16 v[144:147], v[124:127], v[164:167], v[144:147]
	v_mfma_f32_16x16x32_bf16 v[120:123], v[100:103], v[172:175], v[120:123]
	v_mfma_f32_16x16x32_bf16 v[116:119], v[124:127], v[172:175], v[116:119]
	v_mfma_f32_16x16x32_bf16 v[96:99], v[100:103], v[180:183], v[96:99]
	v_mfma_f32_16x16x32_bf16 v[92:95], v[124:127], v[180:183], v[92:95]
	v_mfma_f32_16x16x32_bf16 v[76:79], v[100:103], v[188:191], v[76:79]
	v_mfma_f32_16x16x32_bf16 v[72:75], v[124:127], v[188:191], v[72:75]
	s_setprio 0
	s_setprio 1
	v_mfma_f32_16x16x32_bf16 v[132:135], v[136:139], v[160:163], 0
	v_mfma_f32_16x16x32_bf16 v[128:131], v[148:151], v[160:163], 0
	v_mfma_f32_16x16x32_bf16 v[108:111], v[136:139], v[168:171], 0
	v_mfma_f32_16x16x32_bf16 v[104:107], v[148:151], v[168:171], 0
	v_mfma_f32_16x16x32_bf16 v[84:87], v[136:139], v[176:179], 0
	v_mfma_f32_16x16x32_bf16 v[80:83], v[148:151], v[176:179], 0
	v_mfma_f32_16x16x32_bf16 v[68:71], v[136:139], v[184:187], 0
	v_mfma_f32_16x16x32_bf16 v[64:67], v[148:151], v[184:187], 0
	v_mfma_f32_16x16x32_bf16 v[132:135], v[140:143], v[164:167], v[132:135]
	v_mfma_f32_16x16x32_bf16 v[128:131], v[156:159], v[164:167], v[128:131]
	v_mfma_f32_16x16x32_bf16 v[108:111], v[140:143], v[172:175], v[108:111]
	v_mfma_f32_16x16x32_bf16 v[104:107], v[156:159], v[172:175], v[104:107]
	v_mfma_f32_16x16x32_bf16 v[84:87], v[140:143], v[180:183], v[84:87]
	v_mfma_f32_16x16x32_bf16 v[80:83], v[156:159], v[180:183], v[80:83]
	v_mfma_f32_16x16x32_bf16 v[68:71], v[140:143], v[188:191], v[68:71]
	v_mfma_f32_16x16x32_bf16 v[64:67], v[156:159], v[188:191], v[64:67]
	s_setprio 0
	s_barrier
	s_add_i32 s22, s61, s35
	v_lshl_add_u64 v[212:213], s[26:27], 0, v[192:193]
	s_mov_b32 m0, s22
	ds_read_b128 v[160:163], v250 offset:16384
	ds_read_b128 v[164:167], v250 offset:17408
	ds_read_b128 v[168:171], v250 offset:18432
	ds_read_b128 v[172:175], v250 offset:19456
	ds_read_b128 v[176:179], v250 offset:20480
	ds_read_b128 v[180:183], v250 offset:21504
	ds_read_b128 v[184:187], v250 offset:22528
	ds_read_b128 v[188:191], v250 offset:23552
	global_load_lds_dwordx4 v[212:213], off
	s_add_i32 m0, s22, 0x2000
	s_add_u32 s22, s26, 0xb0000
	v_lshl_add_u64 v[214:215], s[26:27], 0, v[202:203]
	s_addc_u32 s23, s27, 0
	s_add_i32 s61, s68, s35
	global_load_lds_dwordx4 v[214:215], off
	v_lshl_add_u64 v[216:217], s[22:23], 0, v[192:193]
	s_mov_b32 m0, s61
	v_lshl_add_u64 v[218:219], s[28:29], 0, v[204:205]
	global_load_lds_dwordx4 v[216:217], off
	v_lshl_add_u64 v[216:217], s[22:23], 0, v[202:203]
	s_add_i32 m0, s61, 0x2000
	s_nop 0
	global_load_lds_dwordx4 v[216:217], off
	v_lshl_add_u64 v[216:217], s[28:29], 0, v[206:207]
	s_mov_b32 m0, s36
	s_nop 0
	global_load_lds_dwordx4 v[216:217], off
	s_mov_b32 m0, s37
	s_nop 0
	global_load_lds_dwordx4 v[218:219], off
	s_waitcnt vmcnt(8)
	s_waitcnt lgkmcnt(0)
	s_barrier
	s_setprio 1
	s_waitcnt lgkmcnt(0)
	v_mfma_f32_16x16x32_bf16 v[60:63], v[88:91], v[160:163], 0
	v_mfma_f32_16x16x32_bf16 v[56:59], v[112:115], v[160:163], 0
	v_mfma_f32_16x16x32_bf16 v[44:47], v[88:91], v[168:171], 0
	v_mfma_f32_16x16x32_bf16 v[40:43], v[112:115], v[168:171], 0
	v_mfma_f32_16x16x32_bf16 v[28:31], v[88:91], v[176:179], 0
	v_mfma_f32_16x16x32_bf16 v[24:27], v[112:115], v[176:179], 0
	v_mfma_f32_16x16x32_bf16 v[12:15], v[88:91], v[184:187], 0
	v_mfma_f32_16x16x32_bf16 v[8:11], v[112:115], v[184:187], 0
	v_mfma_f32_16x16x32_bf16 v[60:63], v[100:103], v[164:167], v[60:63]
	v_mfma_f32_16x16x32_bf16 v[56:59], v[124:127], v[164:167], v[56:59]
	v_mfma_f32_16x16x32_bf16 v[44:47], v[100:103], v[172:175], v[44:47]
	v_mfma_f32_16x16x32_bf16 v[40:43], v[124:127], v[172:175], v[40:43]
	v_mfma_f32_16x16x32_bf16 v[28:31], v[100:103], v[180:183], v[28:31]
	v_mfma_f32_16x16x32_bf16 v[24:27], v[124:127], v[180:183], v[24:27]
	v_mfma_f32_16x16x32_bf16 v[12:15], v[100:103], v[188:191], v[12:15]
	v_mfma_f32_16x16x32_bf16 v[8:11], v[124:127], v[188:191], v[8:11]
	s_setprio 0
	s_setprio 1
	v_mfma_f32_16x16x32_bf16 v[52:55], v[136:139], v[160:163], 0
	v_mfma_f32_16x16x32_bf16 v[48:51], v[148:151], v[160:163], 0
	v_mfma_f32_16x16x32_bf16 v[36:39], v[136:139], v[168:171], 0
	v_mfma_f32_16x16x32_bf16 v[32:35], v[148:151], v[168:171], 0
	v_mfma_f32_16x16x32_bf16 v[20:23], v[136:139], v[176:179], 0
	v_mfma_f32_16x16x32_bf16 v[16:19], v[148:151], v[176:179], 0
	v_mfma_f32_16x16x32_bf16 v[4:7], v[136:139], v[184:187], 0
	v_mfma_f32_16x16x32_bf16 v[0:3], v[148:151], v[184:187], 0
	v_mfma_f32_16x16x32_bf16 v[52:55], v[140:143], v[164:167], v[52:55]
	v_mfma_f32_16x16x32_bf16 v[48:51], v[156:159], v[164:167], v[48:51]
	v_mfma_f32_16x16x32_bf16 v[36:39], v[140:143], v[172:175], v[36:39]
	v_mfma_f32_16x16x32_bf16 v[32:35], v[156:159], v[172:175], v[32:35]
	v_mfma_f32_16x16x32_bf16 v[20:23], v[140:143], v[180:183], v[20:23]
	v_mfma_f32_16x16x32_bf16 v[16:19], v[156:159], v[180:183], v[16:19]
	v_mfma_f32_16x16x32_bf16 v[4:7], v[140:143], v[188:191], v[4:7]
	v_mfma_f32_16x16x32_bf16 v[0:3], v[156:159], v[188:191], v[0:3]
	s_setprio 0
	s_barrier
	s_add_i32 s61, 0, 0x18000
	s_add_i32 s68, 0, 0x1c000
	v_add_u32_e32 v124, s61, v248
	v_add_u32_e32 v156, s68, v248
	ds_read_b128 v[88:91], v124
	ds_read_b128 v[100:103], v124 offset:1024
	ds_read_b128 v[112:115], v124 offset:2048
	ds_read_b128 v[124:127], v124 offset:3072
	ds_read_b128 v[136:139], v156
	ds_read_b128 v[140:143], v156 offset:1024
	ds_read_b128 v[148:151], v156 offset:2048
	ds_read_b128 v[156:159], v156 offset:3072
	s_add_u32 s22, s28, 0xb0000
	s_addc_u32 s23, s29, 0
	s_mov_b32 m0, s38
	v_lshl_add_u64 v[220:221], s[22:23], 0, v[206:207]
	ds_read_b128 v[160:163], v250 offset:32768
	ds_read_b128 v[164:167], v250 offset:33792
	ds_read_b128 v[168:171], v250 offset:34816
	ds_read_b128 v[172:175], v250 offset:35840
	ds_read_b128 v[176:179], v250 offset:36864
	ds_read_b128 v[180:183], v250 offset:37888
	ds_read_b128 v[184:187], v250 offset:38912
	ds_read_b128 v[188:191], v250 offset:39936
	global_load_lds_dwordx4 v[220:221], off
	v_lshl_add_u64 v[220:221], s[22:23], 0, v[204:205]
	s_mov_b32 m0, s39
	s_nop 0
	global_load_lds_dwordx4 v[220:221], off
	s_waitcnt vmcnt(8)
	s_waitcnt lgkmcnt(0)
	s_barrier
	s_setprio 1
	s_waitcnt lgkmcnt(0)
	v_mfma_f32_16x16x32_bf16 v[152:155], v[88:91], v[160:163], v[152:155]
	v_mfma_f32_16x16x32_bf16 v[144:147], v[112:115], v[160:163], v[144:147]
	v_mfma_f32_16x16x32_bf16 v[120:123], v[88:91], v[168:171], v[120:123]
	v_mfma_f32_16x16x32_bf16 v[116:119], v[112:115], v[168:171], v[116:119]
	v_mfma_f32_16x16x32_bf16 v[96:99], v[88:91], v[176:179], v[96:99]
	v_mfma_f32_16x16x32_bf16 v[92:95], v[112:115], v[176:179], v[92:95]
	v_mfma_f32_16x16x32_bf16 v[76:79], v[88:91], v[184:187], v[76:79]
	v_mfma_f32_16x16x32_bf16 v[72:75], v[112:115], v[184:187], v[72:75]
	v_mfma_f32_16x16x32_bf16 v[152:155], v[100:103], v[164:167], v[152:155]
	v_mfma_f32_16x16x32_bf16 v[144:147], v[124:127], v[164:167], v[144:147]
	v_mfma_f32_16x16x32_bf16 v[120:123], v[100:103], v[172:175], v[120:123]
	v_mfma_f32_16x16x32_bf16 v[116:119], v[124:127], v[172:175], v[116:119]
	v_mfma_f32_16x16x32_bf16 v[96:99], v[100:103], v[180:183], v[96:99]
	v_mfma_f32_16x16x32_bf16 v[92:95], v[124:127], v[180:183], v[92:95]
	v_mfma_f32_16x16x32_bf16 v[76:79], v[100:103], v[188:191], v[76:79]
	v_mfma_f32_16x16x32_bf16 v[72:75], v[124:127], v[188:191], v[72:75]
	s_setprio 0
	s_setprio 1
	v_mfma_f32_16x16x32_bf16 v[132:135], v[136:139], v[160:163], v[132:135]
	v_mfma_f32_16x16x32_bf16 v[128:131], v[148:151], v[160:163], v[128:131]
	v_mfma_f32_16x16x32_bf16 v[108:111], v[136:139], v[168:171], v[108:111]
	v_mfma_f32_16x16x32_bf16 v[104:107], v[148:151], v[168:171], v[104:107]
	v_mfma_f32_16x16x32_bf16 v[84:87], v[136:139], v[176:179], v[84:87]
	v_mfma_f32_16x16x32_bf16 v[80:83], v[148:151], v[176:179], v[80:83]
	v_mfma_f32_16x16x32_bf16 v[68:71], v[136:139], v[184:187], v[68:71]
	v_mfma_f32_16x16x32_bf16 v[64:67], v[148:151], v[184:187], v[64:67]
	v_mfma_f32_16x16x32_bf16 v[132:135], v[140:143], v[164:167], v[132:135]
	v_mfma_f32_16x16x32_bf16 v[128:131], v[156:159], v[164:167], v[128:131]
	v_mfma_f32_16x16x32_bf16 v[108:111], v[140:143], v[172:175], v[108:111]
	v_mfma_f32_16x16x32_bf16 v[104:107], v[156:159], v[172:175], v[104:107]
	v_mfma_f32_16x16x32_bf16 v[84:87], v[140:143], v[180:183], v[84:87]
	v_mfma_f32_16x16x32_bf16 v[80:83], v[156:159], v[180:183], v[80:83]
	v_mfma_f32_16x16x32_bf16 v[68:71], v[140:143], v[188:191], v[68:71]
	v_mfma_f32_16x16x32_bf16 v[64:67], v[156:159], v[188:191], v[64:67]
	s_setprio 0
	s_barrier
	s_add_i32 s22, s61, s35
	v_lshl_add_u64 v[212:213], v[212:213], 0, s[76:77]
	s_mov_b32 m0, s22
	ds_read_b128 v[160:163], v250 offset:49152
	ds_read_b128 v[164:167], v250 offset:50176
	ds_read_b128 v[168:171], v250 offset:51200
	ds_read_b128 v[172:175], v250 offset:52224
	ds_read_b128 v[176:179], v250 offset:53248
	ds_read_b128 v[180:183], v250 offset:54272
	ds_read_b128 v[184:187], v250 offset:55296
	ds_read_b128 v[188:191], v250 offset:56320
	global_load_lds_dwordx4 v[212:213], off
	s_add_i32 m0, s22, 0x2000
	s_add_u32 s22, s26, 0xb0080
	v_lshl_add_u64 v[212:213], v[214:215], 0, s[76:77]
	s_addc_u32 s23, s27, 0
	s_add_i32 s26, s68, s35
	global_load_lds_dwordx4 v[212:213], off
	v_lshl_add_u64 v[212:213], s[22:23], 0, v[192:193]
	s_mov_b32 m0, s26
	s_nop 0
	global_load_lds_dwordx4 v[212:213], off
	v_lshl_add_u64 v[212:213], s[22:23], 0, v[202:203]
	s_add_i32 m0, s26, 0x2000
	s_nop 0
	global_load_lds_dwordx4 v[212:213], off
	v_lshl_add_u64 v[212:213], v[216:217], 0, s[76:77]
	s_mov_b32 m0, s47
	s_nop 0
	global_load_lds_dwordx4 v[212:213], off
	v_lshl_add_u64 v[212:213], v[218:219], 0, s[76:77]
	s_mov_b32 m0, s48
	s_nop 0
	global_load_lds_dwordx4 v[212:213], off
	s_waitcnt vmcnt(8)
	s_waitcnt lgkmcnt(0)
	s_barrier
	s_setprio 1
	s_waitcnt lgkmcnt(0)
	v_mfma_f32_16x16x32_bf16 v[60:63], v[88:91], v[160:163], v[60:63]
	v_mfma_f32_16x16x32_bf16 v[56:59], v[112:115], v[160:163], v[56:59]
	v_mfma_f32_16x16x32_bf16 v[44:47], v[88:91], v[168:171], v[44:47]
	v_mfma_f32_16x16x32_bf16 v[40:43], v[112:115], v[168:171], v[40:43]
	v_mfma_f32_16x16x32_bf16 v[28:31], v[88:91], v[176:179], v[28:31]
	v_mfma_f32_16x16x32_bf16 v[24:27], v[112:115], v[176:179], v[24:27]
	v_mfma_f32_16x16x32_bf16 v[12:15], v[88:91], v[184:187], v[12:15]
	v_mfma_f32_16x16x32_bf16 v[8:11], v[112:115], v[184:187], v[8:11]
	v_mfma_f32_16x16x32_bf16 v[60:63], v[100:103], v[164:167], v[60:63]
	v_mfma_f32_16x16x32_bf16 v[56:59], v[124:127], v[164:167], v[56:59]
	v_mfma_f32_16x16x32_bf16 v[44:47], v[100:103], v[172:175], v[44:47]
	v_mfma_f32_16x16x32_bf16 v[40:43], v[124:127], v[172:175], v[40:43]
	v_mfma_f32_16x16x32_bf16 v[28:31], v[100:103], v[180:183], v[28:31]
	v_mfma_f32_16x16x32_bf16 v[24:27], v[124:127], v[180:183], v[24:27]
	v_mfma_f32_16x16x32_bf16 v[12:15], v[100:103], v[188:191], v[12:15]
	v_mfma_f32_16x16x32_bf16 v[8:11], v[124:127], v[188:191], v[8:11]
	s_setprio 0
	s_setprio 1
	v_mfma_f32_16x16x32_bf16 v[52:55], v[136:139], v[160:163], v[52:55]
	v_mfma_f32_16x16x32_bf16 v[48:51], v[148:151], v[160:163], v[48:51]
	v_mfma_f32_16x16x32_bf16 v[36:39], v[136:139], v[168:171], v[36:39]
	v_mfma_f32_16x16x32_bf16 v[32:35], v[148:151], v[168:171], v[32:35]
	v_mfma_f32_16x16x32_bf16 v[20:23], v[136:139], v[176:179], v[20:23]
	v_mfma_f32_16x16x32_bf16 v[16:19], v[148:151], v[176:179], v[16:19]
	v_mfma_f32_16x16x32_bf16 v[4:7], v[136:139], v[184:187], v[4:7]
	v_mfma_f32_16x16x32_bf16 v[0:3], v[148:151], v[184:187], v[0:3]
	v_mfma_f32_16x16x32_bf16 v[52:55], v[140:143], v[164:167], v[52:55]
	v_mfma_f32_16x16x32_bf16 v[48:51], v[156:159], v[164:167], v[48:51]
	v_mfma_f32_16x16x32_bf16 v[36:39], v[140:143], v[172:175], v[36:39]
	v_mfma_f32_16x16x32_bf16 v[32:35], v[156:159], v[172:175], v[32:35]
	v_mfma_f32_16x16x32_bf16 v[20:23], v[140:143], v[180:183], v[20:23]
	v_mfma_f32_16x16x32_bf16 v[16:19], v[156:159], v[180:183], v[16:19]
	v_mfma_f32_16x16x32_bf16 v[4:7], v[140:143], v[188:191], v[4:7]
	v_mfma_f32_16x16x32_bf16 v[0:3], v[156:159], v[188:191], v[0:3]
	s_setprio 0
	s_barrier
	s_add_i32 s60, s60, 2
	s_add_u32 s56, s56, 0x100
	s_addc_u32 s57, s57, 0
	s_cmp_gt_u32 s60, 41
	s_mov_b64 s[22:23], s[24:25]
